# prune compaction: write address advances by 4 under the pass mask (one VALU less per entry)
# speedup vs baseline: 1.0155x; 1.0011x over previous
.Lp2apr0_iter:
	v_sub_u32_e32 v38, v35, v34
	v_or_b32_e32 v41, 1, v38
	v_ffbh_u32_e32 v41, v41
	v_sub_u32_e32 v41, 26, v41
	v_max_i32_e32 v39, 0, v41
	v_mov_b32_e32 v36, 0
	v_sub_u32_e64 v56, v0, v34 clamp
	v_lshrrev_b32_e32 v56, v39, v56
	v_min_u32_e32 v48, 0x7f, v56
	v_sub_u32_e64 v56, v1, v34 clamp
	v_lshrrev_b32_e32 v56, v39, v56
	v_min_u32_e32 v56, 0x7f, v56
	v_lshl_or_b32 v48, v56, 8, v48
	v_sub_u32_e64 v56, v2, v34 clamp
	v_lshrrev_b32_e32 v56, v39, v56
	v_min_u32_e32 v56, 0x7f, v56
	v_lshl_or_b32 v48, v56, 16, v48
	v_sub_u32_e64 v56, v3, v34 clamp
	v_lshrrev_b32_e32 v56, v39, v56
	v_min_u32_e32 v56, 0x7f, v56
	v_lshl_or_b32 v48, v56, 24, v48
	v_sub_u32_e64 v56, v4, v34 clamp
	v_lshrrev_b32_e32 v56, v39, v56
	v_min_u32_e32 v49, 0x7f, v56
	v_sub_u32_e64 v56, v5, v34 clamp
	v_lshrrev_b32_e32 v56, v39, v56
	v_min_u32_e32 v56, 0x7f, v56
	v_lshl_or_b32 v49, v56, 8, v49
	v_sub_u32_e64 v56, v6, v34 clamp
	v_lshrrev_b32_e32 v56, v39, v56
	v_min_u32_e32 v56, 0x7f, v56
	v_lshl_or_b32 v49, v56, 16, v49
	v_sub_u32_e64 v56, v7, v34 clamp
	v_lshrrev_b32_e32 v56, v39, v56
	v_min_u32_e32 v56, 0x7f, v56
	v_lshl_or_b32 v49, v56, 24, v49
	v_sub_u32_e64 v56, v8, v34 clamp
	v_lshrrev_b32_e32 v56, v39, v56
	v_min_u32_e32 v50, 0x7f, v56
	v_sub_u32_e64 v56, v9, v34 clamp
	v_lshrrev_b32_e32 v56, v39, v56
	v_min_u32_e32 v56, 0x7f, v56
	v_lshl_or_b32 v50, v56, 8, v50
	v_sub_u32_e64 v56, v10, v34 clamp
	v_lshrrev_b32_e32 v56, v39, v56
	v_min_u32_e32 v56, 0x7f, v56
	v_lshl_or_b32 v50, v56, 16, v50
	v_sub_u32_e64 v56, v11, v34 clamp
	v_lshrrev_b32_e32 v56, v39, v56
	v_min_u32_e32 v56, 0x7f, v56
	v_lshl_or_b32 v50, v56, 24, v50
	v_sub_u32_e64 v56, v12, v34 clamp
	v_lshrrev_b32_e32 v56, v39, v56
	v_min_u32_e32 v51, 0x7f, v56
	v_sub_u32_e64 v56, v13, v34 clamp
	v_lshrrev_b32_e32 v56, v39, v56
	v_min_u32_e32 v56, 0x7f, v56
	v_lshl_or_b32 v51, v56, 8, v51
	v_sub_u32_e64 v56, v14, v34 clamp
	v_lshrrev_b32_e32 v56, v39, v56
	v_min_u32_e32 v56, 0x7f, v56
	v_lshl_or_b32 v51, v56, 16, v51
	v_sub_u32_e64 v56, v15, v34 clamp
	v_lshrrev_b32_e32 v56, v39, v56
	v_min_u32_e32 v56, 0x7f, v56
	v_lshl_or_b32 v51, v56, 24, v51
	v_sub_u32_e64 v56, v16, v34 clamp
	v_lshrrev_b32_e32 v56, v39, v56
	v_min_u32_e32 v52, 0x7f, v56
	v_sub_u32_e64 v56, v17, v34 clamp
	v_lshrrev_b32_e32 v56, v39, v56
	v_min_u32_e32 v56, 0x7f, v56
	v_lshl_or_b32 v52, v56, 8, v52
	v_sub_u32_e64 v56, v18, v34 clamp
	v_lshrrev_b32_e32 v56, v39, v56
	v_min_u32_e32 v56, 0x7f, v56
	v_lshl_or_b32 v52, v56, 16, v52
	v_sub_u32_e64 v56, v19, v34 clamp
	v_lshrrev_b32_e32 v56, v39, v56
	v_min_u32_e32 v56, 0x7f, v56
	v_lshl_or_b32 v52, v56, 24, v52
	v_sub_u32_e64 v56, v20, v34 clamp
	v_lshrrev_b32_e32 v56, v39, v56
	v_min_u32_e32 v53, 0x7f, v56
	v_sub_u32_e64 v56, v21, v34 clamp
	v_lshrrev_b32_e32 v56, v39, v56
	v_min_u32_e32 v56, 0x7f, v56
	v_lshl_or_b32 v53, v56, 8, v53
	v_sub_u32_e64 v56, v22, v34 clamp
	v_lshrrev_b32_e32 v56, v39, v56
	v_min_u32_e32 v56, 0x7f, v56
	v_lshl_or_b32 v53, v56, 16, v53
	v_sub_u32_e64 v56, v23, v34 clamp
	v_lshrrev_b32_e32 v56, v39, v56
	v_min_u32_e32 v56, 0x7f, v56
	v_lshl_or_b32 v53, v56, 24, v53
	v_sub_u32_e64 v56, v24, v34 clamp
	v_lshrrev_b32_e32 v56, v39, v56
	v_min_u32_e32 v54, 0x7f, v56
	v_sub_u32_e64 v56, v25, v34 clamp
	v_lshrrev_b32_e32 v56, v39, v56
	v_min_u32_e32 v56, 0x7f, v56
	v_lshl_or_b32 v54, v56, 8, v54
	v_sub_u32_e64 v56, v26, v34 clamp
	v_lshrrev_b32_e32 v56, v39, v56
	v_min_u32_e32 v56, 0x7f, v56
	v_lshl_or_b32 v54, v56, 16, v54
	v_sub_u32_e64 v56, v27, v34 clamp
	v_lshrrev_b32_e32 v56, v39, v56
	v_min_u32_e32 v56, 0x7f, v56
	v_lshl_or_b32 v54, v56, 24, v54
	v_sub_u32_e64 v56, v28, v34 clamp
	v_lshrrev_b32_e32 v56, v39, v56
	v_min_u32_e32 v55, 0x7f, v56
	v_sub_u32_e64 v56, v29, v34 clamp
	v_lshrrev_b32_e32 v56, v39, v56
	v_min_u32_e32 v56, 0x7f, v56
	v_lshl_or_b32 v55, v56, 8, v55
	v_sub_u32_e64 v56, v30, v34 clamp
	v_lshrrev_b32_e32 v56, v39, v56
	v_min_u32_e32 v56, 0x7f, v56
	v_lshl_or_b32 v55, v56, 16, v55
	v_sub_u32_e64 v56, v31, v34 clamp
	v_lshrrev_b32_e32 v56, v39, v56
	v_min_u32_e32 v56, 0x7f, v56
	v_lshl_or_b32 v55, v56, 24, v55
	v_or_b32_e32 v42, 0x20202020, v36
	v_subrev_u32_e32 v43, 0x80808080, v42
	v_mov_b32_e32 v44, 0
	v_sub_u32_e32 v41, v48, v43
	v_and_b32_e32 v41, 0x80808080, v41
	v_bcnt_u32_b32 v44, v41, v44
	v_sub_u32_e32 v45, v49, v43
	v_and_b32_e32 v45, 0x80808080, v45
	v_bcnt_u32_b32 v44, v45, v44
	v_sub_u32_e32 v41, v50, v43
	v_and_b32_e32 v41, 0x80808080, v41
	v_bcnt_u32_b32 v44, v41, v44
	v_sub_u32_e32 v45, v51, v43
	v_and_b32_e32 v45, 0x80808080, v45
	v_bcnt_u32_b32 v44, v45, v44
	v_sub_u32_e32 v41, v52, v43
	v_and_b32_e32 v41, 0x80808080, v41
	v_bcnt_u32_b32 v44, v41, v44
	v_sub_u32_e32 v45, v53, v43
	v_and_b32_e32 v45, 0x80808080, v45
	v_bcnt_u32_b32 v44, v45, v44
	v_sub_u32_e32 v41, v54, v43
	v_and_b32_e32 v41, 0x80808080, v41
	v_bcnt_u32_b32 v44, v41, v44
	v_sub_u32_e32 v45, v55, v43
	v_and_b32_e32 v45, 0x80808080, v45
	v_bcnt_u32_b32 v44, v45, v44
	v_mov_b32_e32 v45, v44
	s_nop 1
	v_add_u32_dpp v45, v45, v45 row_ror:1 row_mask:0xf bank_mask:0xf
	s_nop 1
	v_add_u32_dpp v45, v45, v45 row_ror:2 row_mask:0xf bank_mask:0xf
	s_nop 1
	v_add_u32_dpp v45, v45, v45 row_ror:4 row_mask:0xf bank_mask:0xf
	s_nop 1
	v_add_u32_dpp v45, v45, v45 row_ror:8 row_mask:0xf bank_mask:0xf
	s_nop 0
	v_cmp_le_u32_e32 vcc, 0x100, v45
	s_nop 1
	v_cndmask_b32_e32 v36, v36, v42, vcc
	v_cndmask_b32_e32 v46, v46, v45, vcc
	v_cndmask_b32_e32 v47, v47, v44, vcc
	v_or_b32_e32 v42, 0x10101010, v36
	v_subrev_u32_e32 v43, 0x80808080, v42
	v_mov_b32_e32 v44, 0
	v_sub_u32_e32 v41, v48, v43
	v_and_b32_e32 v41, 0x80808080, v41
	v_bcnt_u32_b32 v44, v41, v44
	v_sub_u32_e32 v45, v49, v43
	v_and_b32_e32 v45, 0x80808080, v45
	v_bcnt_u32_b32 v44, v45, v44
	v_sub_u32_e32 v41, v50, v43
	v_and_b32_e32 v41, 0x80808080, v41
	v_bcnt_u32_b32 v44, v41, v44
	v_sub_u32_e32 v45, v51, v43
	v_and_b32_e32 v45, 0x80808080, v45
	v_bcnt_u32_b32 v44, v45, v44
	v_sub_u32_e32 v41, v52, v43
	v_and_b32_e32 v41, 0x80808080, v41
	v_bcnt_u32_b32 v44, v41, v44
	v_sub_u32_e32 v45, v53, v43
	v_and_b32_e32 v45, 0x80808080, v45
	v_bcnt_u32_b32 v44, v45, v44
	v_sub_u32_e32 v41, v54, v43
	v_and_b32_e32 v41, 0x80808080, v41
	v_bcnt_u32_b32 v44, v41, v44
	v_sub_u32_e32 v45, v55, v43
	v_and_b32_e32 v45, 0x80808080, v45
	v_bcnt_u32_b32 v44, v45, v44
	v_mov_b32_e32 v45, v44
	s_nop 1
	v_add_u32_dpp v45, v45, v45 row_ror:1 row_mask:0xf bank_mask:0xf
	s_nop 1
	v_add_u32_dpp v45, v45, v45 row_ror:2 row_mask:0xf bank_mask:0xf
	s_nop 1
	v_add_u32_dpp v45, v45, v45 row_ror:4 row_mask:0xf bank_mask:0xf
	s_nop 1
	v_add_u32_dpp v45, v45, v45 row_ror:8 row_mask:0xf bank_mask:0xf
	s_nop 0
	v_cmp_le_u32_e32 vcc, 0x100, v45
	s_nop 1
	v_cndmask_b32_e32 v36, v36, v42, vcc
	v_cndmask_b32_e32 v46, v46, v45, vcc
	v_cndmask_b32_e32 v47, v47, v44, vcc
	v_or_b32_e32 v42, 0x8080808, v36
	v_subrev_u32_e32 v43, 0x80808080, v42
	v_mov_b32_e32 v44, 0
	v_sub_u32_e32 v41, v48, v43
	v_and_b32_e32 v41, 0x80808080, v41
	v_bcnt_u32_b32 v44, v41, v44
	v_sub_u32_e32 v45, v49, v43
	v_and_b32_e32 v45, 0x80808080, v45
	v_bcnt_u32_b32 v44, v45, v44
	v_sub_u32_e32 v41, v50, v43
	v_and_b32_e32 v41, 0x80808080, v41
	v_bcnt_u32_b32 v44, v41, v44
	v_sub_u32_e32 v45, v51, v43
	v_and_b32_e32 v45, 0x80808080, v45
	v_bcnt_u32_b32 v44, v45, v44
	v_sub_u32_e32 v41, v52, v43
	v_and_b32_e32 v41, 0x80808080, v41
	v_bcnt_u32_b32 v44, v41, v44
	v_sub_u32_e32 v45, v53, v43
	v_and_b32_e32 v45, 0x80808080, v45
	v_bcnt_u32_b32 v44, v45, v44
	v_sub_u32_e32 v41, v54, v43
	v_and_b32_e32 v41, 0x80808080, v41
	v_bcnt_u32_b32 v44, v41, v44
	v_sub_u32_e32 v45, v55, v43
	v_and_b32_e32 v45, 0x80808080, v45
	v_bcnt_u32_b32 v44, v45, v44
	v_mov_b32_e32 v45, v44
	s_nop 1
	v_add_u32_dpp v45, v45, v45 row_ror:1 row_mask:0xf bank_mask:0xf
	s_nop 1
	v_add_u32_dpp v45, v45, v45 row_ror:2 row_mask:0xf bank_mask:0xf
	s_nop 1
	v_add_u32_dpp v45, v45, v45 row_ror:4 row_mask:0xf bank_mask:0xf
	s_nop 1
	v_add_u32_dpp v45, v45, v45 row_ror:8 row_mask:0xf bank_mask:0xf
	s_nop 0
	v_cmp_le_u32_e32 vcc, 0x100, v45
	s_nop 1
	v_cndmask_b32_e32 v36, v36, v42, vcc
	v_cndmask_b32_e32 v46, v46, v45, vcc
	v_cndmask_b32_e32 v47, v47, v44, vcc
	v_or_b32_e32 v42, 0x4040404, v36
	v_subrev_u32_e32 v43, 0x80808080, v42
	v_mov_b32_e32 v44, 0
	v_sub_u32_e32 v41, v48, v43
	v_and_b32_e32 v41, 0x80808080, v41
	v_bcnt_u32_b32 v44, v41, v44
	v_sub_u32_e32 v45, v49, v43
	v_and_b32_e32 v45, 0x80808080, v45
	v_bcnt_u32_b32 v44, v45, v44
	v_sub_u32_e32 v41, v50, v43
	v_and_b32_e32 v41, 0x80808080, v41
	v_bcnt_u32_b32 v44, v41, v44
	v_sub_u32_e32 v45, v51, v43
	v_and_b32_e32 v45, 0x80808080, v45
	v_bcnt_u32_b32 v44, v45, v44
	v_sub_u32_e32 v41, v52, v43
	v_and_b32_e32 v41, 0x80808080, v41
	v_bcnt_u32_b32 v44, v41, v44
	v_sub_u32_e32 v45, v53, v43
	v_and_b32_e32 v45, 0x80808080, v45
	v_bcnt_u32_b32 v44, v45, v44
	v_sub_u32_e32 v41, v54, v43
	v_and_b32_e32 v41, 0x80808080, v41
	v_bcnt_u32_b32 v44, v41, v44
	v_sub_u32_e32 v45, v55, v43
	v_and_b32_e32 v45, 0x80808080, v45
	v_bcnt_u32_b32 v44, v45, v44
	v_mov_b32_e32 v45, v44
	s_nop 1
	v_add_u32_dpp v45, v45, v45 row_ror:1 row_mask:0xf bank_mask:0xf
	s_nop 1
	v_add_u32_dpp v45, v45, v45 row_ror:2 row_mask:0xf bank_mask:0xf
	s_nop 1
	v_add_u32_dpp v45, v45, v45 row_ror:4 row_mask:0xf bank_mask:0xf
	s_nop 1
	v_add_u32_dpp v45, v45, v45 row_ror:8 row_mask:0xf bank_mask:0xf
	s_nop 0
	v_cmp_le_u32_e32 vcc, 0x100, v45
	s_nop 1
	v_cndmask_b32_e32 v36, v36, v42, vcc
	v_cndmask_b32_e32 v46, v46, v45, vcc
	v_cndmask_b32_e32 v47, v47, v44, vcc
	v_or_b32_e32 v42, 0x2020202, v36
	v_subrev_u32_e32 v43, 0x80808080, v42
	v_mov_b32_e32 v44, 0
	v_sub_u32_e32 v41, v48, v43
	v_and_b32_e32 v41, 0x80808080, v41
	v_bcnt_u32_b32 v44, v41, v44
	v_sub_u32_e32 v45, v49, v43
	v_and_b32_e32 v45, 0x80808080, v45
	v_bcnt_u32_b32 v44, v45, v44
	v_sub_u32_e32 v41, v50, v43
	v_and_b32_e32 v41, 0x80808080, v41
	v_bcnt_u32_b32 v44, v41, v44
	v_sub_u32_e32 v45, v51, v43
	v_and_b32_e32 v45, 0x80808080, v45
	v_bcnt_u32_b32 v44, v45, v44
	v_sub_u32_e32 v41, v52, v43
	v_and_b32_e32 v41, 0x80808080, v41
	v_bcnt_u32_b32 v44, v41, v44
	v_sub_u32_e32 v45, v53, v43
	v_and_b32_e32 v45, 0x80808080, v45
	v_bcnt_u32_b32 v44, v45, v44
	v_sub_u32_e32 v41, v54, v43
	v_and_b32_e32 v41, 0x80808080, v41
	v_bcnt_u32_b32 v44, v41, v44
	v_sub_u32_e32 v45, v55, v43
	v_and_b32_e32 v45, 0x80808080, v45
	v_bcnt_u32_b32 v44, v45, v44
	v_mov_b32_e32 v45, v44
	s_nop 1
	v_add_u32_dpp v45, v45, v45 row_ror:1 row_mask:0xf bank_mask:0xf
	s_nop 1
	v_add_u32_dpp v45, v45, v45 row_ror:2 row_mask:0xf bank_mask:0xf
	s_nop 1
	v_add_u32_dpp v45, v45, v45 row_ror:4 row_mask:0xf bank_mask:0xf
	s_nop 1
	v_add_u32_dpp v45, v45, v45 row_ror:8 row_mask:0xf bank_mask:0xf
	s_nop 0
	v_cmp_le_u32_e32 vcc, 0x100, v45
	s_nop 1
	v_cndmask_b32_e32 v36, v36, v42, vcc
	v_cndmask_b32_e32 v46, v46, v45, vcc
	v_cndmask_b32_e32 v47, v47, v44, vcc
	v_or_b32_e32 v42, 0x1010101, v36
	v_subrev_u32_e32 v43, 0x80808080, v42
	v_mov_b32_e32 v44, 0
	v_sub_u32_e32 v41, v48, v43
	v_and_b32_e32 v41, 0x80808080, v41
	v_bcnt_u32_b32 v44, v41, v44
	v_sub_u32_e32 v45, v49, v43
	v_and_b32_e32 v45, 0x80808080, v45
	v_bcnt_u32_b32 v44, v45, v44
	v_sub_u32_e32 v41, v50, v43
	v_and_b32_e32 v41, 0x80808080, v41
	v_bcnt_u32_b32 v44, v41, v44
	v_sub_u32_e32 v45, v51, v43
	v_and_b32_e32 v45, 0x80808080, v45
	v_bcnt_u32_b32 v44, v45, v44
	v_sub_u32_e32 v41, v52, v43
	v_and_b32_e32 v41, 0x80808080, v41
	v_bcnt_u32_b32 v44, v41, v44
	v_sub_u32_e32 v45, v53, v43
	v_and_b32_e32 v45, 0x80808080, v45
	v_bcnt_u32_b32 v44, v45, v44
	v_sub_u32_e32 v41, v54, v43
	v_and_b32_e32 v41, 0x80808080, v41
	v_bcnt_u32_b32 v44, v41, v44
	v_sub_u32_e32 v45, v55, v43
	v_and_b32_e32 v45, 0x80808080, v45
	v_bcnt_u32_b32 v44, v45, v44
	v_mov_b32_e32 v45, v44
	s_nop 1
	v_add_u32_dpp v45, v45, v45 row_ror:1 row_mask:0xf bank_mask:0xf
	s_nop 1
	v_add_u32_dpp v45, v45, v45 row_ror:2 row_mask:0xf bank_mask:0xf
	s_nop 1
	v_add_u32_dpp v45, v45, v45 row_ror:4 row_mask:0xf bank_mask:0xf
	s_nop 1
	v_add_u32_dpp v45, v45, v45 row_ror:8 row_mask:0xf bank_mask:0xf
	s_nop 0
	v_cmp_le_u32_e32 vcc, 0x100, v45
	s_nop 1
	v_cndmask_b32_e32 v36, v36, v42, vcc
	v_cndmask_b32_e32 v46, v46, v45, vcc
	v_cndmask_b32_e32 v47, v47, v44, vcc
	v_and_b32_e32 v41, 0x7f, v36
	v_lshlrev_b32_e32 v41, v39, v41
	v_add_u32_e32 v41, v34, v41
	v_cmp_ge_u32_e32 vcc, 0x120, v46
	v_cmp_eq_u32_e64 s[0:1], 0, v39
	v_lshlrev_b32_e32 v42, v39, v200
	v_add_u32_e32 v42, -1, v42
	s_or_b64 vcc, vcc, s[0:1]
	s_andn2_b64 s[0:1], vcc, s[50:51]
	s_nor_b64 s[2:3], vcc, s[50:51]
	s_or_b64 s[50:51], s[50:51], vcc
	v_add_u32_e64 v42, v41, v42 clamp
	v_min_u32_e32 v42, v42, v35
	v_cndmask_b32_e64 v37, v37, v41, s[0:1]
	v_cndmask_b32_e64 v62, v62, v47, s[0:1]
	v_cndmask_b32_e64 v35, v35, v42, s[2:3]
	v_cndmask_b32_e64 v34, v34, v41, s[2:3]
	s_cmp_eq_u64 s[50:51], -1
	s_cbranch_scc0 .Lp2apr0_iter
	s_mov_b64 exec, s[22:23]
	v_mov_b32_e32 v61, v62
	s_nop 1
	v_add_u32_dpp v61, v61, v61 row_shr:1 row_mask:0xf bank_mask:0xf bound_ctrl:1
	s_nop 1
	v_add_u32_dpp v61, v61, v61 row_shr:2 row_mask:0xf bank_mask:0xf bound_ctrl:1
	s_nop 1
	v_add_u32_dpp v61, v61, v61 row_shr:4 row_mask:0xf bank_mask:0xf bound_ctrl:1
	s_nop 1
	v_add_u32_dpp v61, v61, v61 row_shr:8 row_mask:0xf bank_mask:0xf bound_ctrl:1
	v_sub_u32_e32 v62, v61, v62
	v_lshl_add_u32 v41, v62, 2, v59
	v_add_u32_e32 v41, -4, v41
	v_cmpx_ge_u32_e32 vcc, v0, v37
	v_add_u32_e32 v41, 4, v41
	ds_write_b32 v41, v0
	s_mov_b64 exec, s[22:23]
	v_cmpx_ge_u32_e32 vcc, v1, v37
	v_add_u32_e32 v41, 4, v41
	ds_write_b32 v41, v1
	s_mov_b64 exec, s[22:23]
	v_cmpx_ge_u32_e32 vcc, v2, v37
	v_add_u32_e32 v41, 4, v41
	ds_write_b32 v41, v2
	s_mov_b64 exec, s[22:23]
	v_cmpx_ge_u32_e32 vcc, v3, v37
	v_add_u32_e32 v41, 4, v41
	ds_write_b32 v41, v3
	s_mov_b64 exec, s[22:23]
	v_cmpx_ge_u32_e32 vcc, v4, v37
	v_add_u32_e32 v41, 4, v41
	ds_write_b32 v41, v4
	s_mov_b64 exec, s[22:23]
	v_cmpx_ge_u32_e32 vcc, v5, v37
	v_add_u32_e32 v41, 4, v41
	ds_write_b32 v41, v5
	s_mov_b64 exec, s[22:23]
	v_cmpx_ge_u32_e32 vcc, v6, v37
	v_add_u32_e32 v41, 4, v41
	ds_write_b32 v41, v6
	s_mov_b64 exec, s[22:23]
	v_cmpx_ge_u32_e32 vcc, v7, v37
	v_add_u32_e32 v41, 4, v41
	ds_write_b32 v41, v7
	s_mov_b64 exec, s[22:23]
	v_cmpx_ge_u32_e32 vcc, v8, v37
	v_add_u32_e32 v41, 4, v41
	ds_write_b32 v41, v8
	s_mov_b64 exec, s[22:23]
	v_cmpx_ge_u32_e32 vcc, v9, v37
	v_add_u32_e32 v41, 4, v41
	ds_write_b32 v41, v9
	s_mov_b64 exec, s[22:23]
	v_cmpx_ge_u32_e32 vcc, v10, v37
	v_add_u32_e32 v41, 4, v41
	ds_write_b32 v41, v10
	s_mov_b64 exec, s[22:23]
	v_cmpx_ge_u32_e32 vcc, v11, v37
	v_add_u32_e32 v41, 4, v41
	ds_write_b32 v41, v11
	s_mov_b64 exec, s[22:23]
	v_cmpx_ge_u32_e32 vcc, v12, v37
	v_add_u32_e32 v41, 4, v41
	ds_write_b32 v41, v12
	s_mov_b64 exec, s[22:23]
	v_cmpx_ge_u32_e32 vcc, v13, v37
	v_add_u32_e32 v41, 4, v41
	ds_write_b32 v41, v13
	s_mov_b64 exec, s[22:23]
	v_cmpx_ge_u32_e32 vcc, v14, v37
	v_add_u32_e32 v41, 4, v41
	ds_write_b32 v41, v14
	s_mov_b64 exec, s[22:23]
	v_cmpx_ge_u32_e32 vcc, v15, v37
	v_add_u32_e32 v41, 4, v41
	ds_write_b32 v41, v15
	s_mov_b64 exec, s[22:23]
	v_cmpx_ge_u32_e32 vcc, v16, v37
	v_add_u32_e32 v41, 4, v41
	ds_write_b32 v41, v16
	s_mov_b64 exec, s[22:23]
	v_cmpx_ge_u32_e32 vcc, v17, v37
	v_add_u32_e32 v41, 4, v41
	ds_write_b32 v41, v17
	s_mov_b64 exec, s[22:23]
	v_cmpx_ge_u32_e32 vcc, v18, v37
	v_add_u32_e32 v41, 4, v41
	ds_write_b32 v41, v18
	s_mov_b64 exec, s[22:23]
	v_cmpx_ge_u32_e32 vcc, v19, v37
	v_add_u32_e32 v41, 4, v41
	ds_write_b32 v41, v19
	s_mov_b64 exec, s[22:23]
	v_cmpx_ge_u32_e32 vcc, v20, v37
	v_add_u32_e32 v41, 4, v41
	ds_write_b32 v41, v20
	s_mov_b64 exec, s[22:23]
	v_cmpx_ge_u32_e32 vcc, v21, v37
	v_add_u32_e32 v41, 4, v41
	ds_write_b32 v41, v21
	s_mov_b64 exec, s[22:23]
	v_cmpx_ge_u32_e32 vcc, v22, v37
	v_add_u32_e32 v41, 4, v41
	ds_write_b32 v41, v22
	s_mov_b64 exec, s[22:23]
	v_cmpx_ge_u32_e32 vcc, v23, v37
	v_add_u32_e32 v41, 4, v41
	ds_write_b32 v41, v23
	s_mov_b64 exec, s[22:23]
	v_cmpx_ge_u32_e32 vcc, v24, v37
	v_add_u32_e32 v41, 4, v41
	ds_write_b32 v41, v24
	s_mov_b64 exec, s[22:23]
	v_cmpx_ge_u32_e32 vcc, v25, v37
	v_add_u32_e32 v41, 4, v41
	ds_write_b32 v41, v25
	s_mov_b64 exec, s[22:23]
	v_cmpx_ge_u32_e32 vcc, v26, v37
	v_add_u32_e32 v41, 4, v41
	ds_write_b32 v41, v26
	s_mov_b64 exec, s[22:23]
	v_cmpx_ge_u32_e32 vcc, v27, v37
	v_add_u32_e32 v41, 4, v41
	ds_write_b32 v41, v27
	s_mov_b64 exec, s[22:23]
	v_cmpx_ge_u32_e32 vcc, v28, v37
	v_add_u32_e32 v41, 4, v41
	ds_write_b32 v41, v28
	s_mov_b64 exec, s[22:23]
	v_cmpx_ge_u32_e32 vcc, v29, v37
	v_add_u32_e32 v41, 4, v41
	ds_write_b32 v41, v29
	s_mov_b64 exec, s[22:23]
	v_cmpx_ge_u32_e32 vcc, v30, v37
	v_add_u32_e32 v41, 4, v41
	ds_write_b32 v41, v30
	s_mov_b64 exec, s[22:23]
	v_cmpx_ge_u32_e32 vcc, v31, v37
	v_add_u32_e32 v41, 4, v41
	ds_write_b32 v41, v31
	s_mov_b64 exec, s[22:23]
	s_mov_b64 exec, -1
	v_and_b32_e32 v41, 0xffffe000, v37
	v_ashrrev_i32_e32 v42, 31, v41
	v_not_b32_e32 v42, v42
	v_or_b32_e32 v42, 0x80000000, v42
	v_xor_b32_e32 v63, v41, v42
	s_cmpk_lt_i32 s78, 0x121
	s_cbranch_scc1 .Lp2apr0_o0
	v_readlane_b32 s0, v63, 0
	v_readlane_b32 s73, v37, 0
	v_readlane_b32 s78, v61, 15
	v_mov_b32_e32 v231, s0

.Lp2apr1_iter:
	v_sub_u32_e32 v38, v35, v34
	v_or_b32_e32 v41, 1, v38
	v_ffbh_u32_e32 v41, v41
	v_sub_u32_e32 v41, 26, v41
	v_max_i32_e32 v39, 0, v41
	v_mov_b32_e32 v36, 0
	v_sub_u32_e64 v56, v0, v34 clamp
	v_lshrrev_b32_e32 v56, v39, v56
	v_min_u32_e32 v48, 0x7f, v56
	v_sub_u32_e64 v56, v1, v34 clamp
	v_lshrrev_b32_e32 v56, v39, v56
	v_min_u32_e32 v56, 0x7f, v56
	v_lshl_or_b32 v48, v56, 8, v48
	v_sub_u32_e64 v56, v2, v34 clamp
	v_lshrrev_b32_e32 v56, v39, v56
	v_min_u32_e32 v56, 0x7f, v56
	v_lshl_or_b32 v48, v56, 16, v48
	v_sub_u32_e64 v56, v3, v34 clamp
	v_lshrrev_b32_e32 v56, v39, v56
	v_min_u32_e32 v56, 0x7f, v56
	v_lshl_or_b32 v48, v56, 24, v48
	v_sub_u32_e64 v56, v4, v34 clamp
	v_lshrrev_b32_e32 v56, v39, v56
	v_min_u32_e32 v49, 0x7f, v56
	v_sub_u32_e64 v56, v5, v34 clamp
	v_lshrrev_b32_e32 v56, v39, v56
	v_min_u32_e32 v56, 0x7f, v56
	v_lshl_or_b32 v49, v56, 8, v49
	v_sub_u32_e64 v56, v6, v34 clamp
	v_lshrrev_b32_e32 v56, v39, v56
	v_min_u32_e32 v56, 0x7f, v56
	v_lshl_or_b32 v49, v56, 16, v49
	v_sub_u32_e64 v56, v7, v34 clamp
	v_lshrrev_b32_e32 v56, v39, v56
	v_min_u32_e32 v56, 0x7f, v56
	v_lshl_or_b32 v49, v56, 24, v49
	v_sub_u32_e64 v56, v8, v34 clamp
	v_lshrrev_b32_e32 v56, v39, v56
	v_min_u32_e32 v50, 0x7f, v56
	v_sub_u32_e64 v56, v9, v34 clamp
	v_lshrrev_b32_e32 v56, v39, v56
	v_min_u32_e32 v56, 0x7f, v56
	v_lshl_or_b32 v50, v56, 8, v50
	v_sub_u32_e64 v56, v10, v34 clamp
	v_lshrrev_b32_e32 v56, v39, v56
	v_min_u32_e32 v56, 0x7f, v56
	v_lshl_or_b32 v50, v56, 16, v50
	v_sub_u32_e64 v56, v11, v34 clamp
	v_lshrrev_b32_e32 v56, v39, v56
	v_min_u32_e32 v56, 0x7f, v56
	v_lshl_or_b32 v50, v56, 24, v50
	v_sub_u32_e64 v56, v12, v34 clamp
	v_lshrrev_b32_e32 v56, v39, v56
	v_min_u32_e32 v51, 0x7f, v56
	v_sub_u32_e64 v56, v13, v34 clamp
	v_lshrrev_b32_e32 v56, v39, v56
	v_min_u32_e32 v56, 0x7f, v56
	v_lshl_or_b32 v51, v56, 8, v51
	v_sub_u32_e64 v56, v14, v34 clamp
	v_lshrrev_b32_e32 v56, v39, v56
	v_min_u32_e32 v56, 0x7f, v56
	v_lshl_or_b32 v51, v56, 16, v51
	v_sub_u32_e64 v56, v15, v34 clamp
	v_lshrrev_b32_e32 v56, v39, v56
	v_min_u32_e32 v56, 0x7f, v56
	v_lshl_or_b32 v51, v56, 24, v51
	v_sub_u32_e64 v56, v16, v34 clamp
	v_lshrrev_b32_e32 v56, v39, v56
	v_min_u32_e32 v52, 0x7f, v56
	v_sub_u32_e64 v56, v17, v34 clamp
	v_lshrrev_b32_e32 v56, v39, v56
	v_min_u32_e32 v56, 0x7f, v56
	v_lshl_or_b32 v52, v56, 8, v52
	v_sub_u32_e64 v56, v18, v34 clamp
	v_lshrrev_b32_e32 v56, v39, v56
	v_min_u32_e32 v56, 0x7f, v56
	v_lshl_or_b32 v52, v56, 16, v52
	v_sub_u32_e64 v56, v19, v34 clamp
	v_lshrrev_b32_e32 v56, v39, v56
	v_min_u32_e32 v56, 0x7f, v56
	v_lshl_or_b32 v52, v56, 24, v52
	v_sub_u32_e64 v56, v20, v34 clamp
	v_lshrrev_b32_e32 v56, v39, v56
	v_min_u32_e32 v53, 0x7f, v56
	v_sub_u32_e64 v56, v21, v34 clamp
	v_lshrrev_b32_e32 v56, v39, v56
	v_min_u32_e32 v56, 0x7f, v56
	v_lshl_or_b32 v53, v56, 8, v53
	v_sub_u32_e64 v56, v22, v34 clamp
	v_lshrrev_b32_e32 v56, v39, v56
	v_min_u32_e32 v56, 0x7f, v56
	v_lshl_or_b32 v53, v56, 16, v53
	v_sub_u32_e64 v56, v23, v34 clamp
	v_lshrrev_b32_e32 v56, v39, v56
	v_min_u32_e32 v56, 0x7f, v56
	v_lshl_or_b32 v53, v56, 24, v53
	v_sub_u32_e64 v56, v24, v34 clamp
	v_lshrrev_b32_e32 v56, v39, v56
	v_min_u32_e32 v54, 0x7f, v56
	v_sub_u32_e64 v56, v25, v34 clamp
	v_lshrrev_b32_e32 v56, v39, v56
	v_min_u32_e32 v56, 0x7f, v56
	v_lshl_or_b32 v54, v56, 8, v54
	v_sub_u32_e64 v56, v26, v34 clamp
	v_lshrrev_b32_e32 v56, v39, v56
	v_min_u32_e32 v56, 0x7f, v56
	v_lshl_or_b32 v54, v56, 16, v54
	v_sub_u32_e64 v56, v27, v34 clamp
	v_lshrrev_b32_e32 v56, v39, v56
	v_min_u32_e32 v56, 0x7f, v56
	v_lshl_or_b32 v54, v56, 24, v54
	v_sub_u32_e64 v56, v28, v34 clamp
	v_lshrrev_b32_e32 v56, v39, v56
	v_min_u32_e32 v55, 0x7f, v56
	v_sub_u32_e64 v56, v29, v34 clamp
	v_lshrrev_b32_e32 v56, v39, v56
	v_min_u32_e32 v56, 0x7f, v56
	v_lshl_or_b32 v55, v56, 8, v55
	v_sub_u32_e64 v56, v30, v34 clamp
	v_lshrrev_b32_e32 v56, v39, v56
	v_min_u32_e32 v56, 0x7f, v56
	v_lshl_or_b32 v55, v56, 16, v55
	v_sub_u32_e64 v56, v31, v34 clamp
	v_lshrrev_b32_e32 v56, v39, v56
	v_min_u32_e32 v56, 0x7f, v56
	v_lshl_or_b32 v55, v56, 24, v55
	v_or_b32_e32 v42, 0x20202020, v36
	v_subrev_u32_e32 v43, 0x80808080, v42
	v_mov_b32_e32 v44, 0
	v_sub_u32_e32 v41, v48, v43
	v_and_b32_e32 v41, 0x80808080, v41
	v_bcnt_u32_b32 v44, v41, v44
	v_sub_u32_e32 v45, v49, v43
	v_and_b32_e32 v45, 0x80808080, v45
	v_bcnt_u32_b32 v44, v45, v44
	v_sub_u32_e32 v41, v50, v43
	v_and_b32_e32 v41, 0x80808080, v41
	v_bcnt_u32_b32 v44, v41, v44
	v_sub_u32_e32 v45, v51, v43
	v_and_b32_e32 v45, 0x80808080, v45
	v_bcnt_u32_b32 v44, v45, v44
	v_sub_u32_e32 v41, v52, v43
	v_and_b32_e32 v41, 0x80808080, v41
	v_bcnt_u32_b32 v44, v41, v44
	v_sub_u32_e32 v45, v53, v43
	v_and_b32_e32 v45, 0x80808080, v45
	v_bcnt_u32_b32 v44, v45, v44
	v_sub_u32_e32 v41, v54, v43
	v_and_b32_e32 v41, 0x80808080, v41
	v_bcnt_u32_b32 v44, v41, v44
	v_sub_u32_e32 v45, v55, v43
	v_and_b32_e32 v45, 0x80808080, v45
	v_bcnt_u32_b32 v44, v45, v44
	v_mov_b32_e32 v45, v44
	s_nop 1
	v_add_u32_dpp v45, v45, v45 row_ror:1 row_mask:0xf bank_mask:0xf
	s_nop 1
	v_add_u32_dpp v45, v45, v45 row_ror:2 row_mask:0xf bank_mask:0xf
	s_nop 1
	v_add_u32_dpp v45, v45, v45 row_ror:4 row_mask:0xf bank_mask:0xf
	s_nop 1
	v_add_u32_dpp v45, v45, v45 row_ror:8 row_mask:0xf bank_mask:0xf
	s_nop 0
	v_cmp_le_u32_e32 vcc, 0x100, v45
	s_nop 1
	v_cndmask_b32_e32 v36, v36, v42, vcc
	v_cndmask_b32_e32 v46, v46, v45, vcc
	v_cndmask_b32_e32 v47, v47, v44, vcc
	v_or_b32_e32 v42, 0x10101010, v36
	v_subrev_u32_e32 v43, 0x80808080, v42
	v_mov_b32_e32 v44, 0
	v_sub_u32_e32 v41, v48, v43
	v_and_b32_e32 v41, 0x80808080, v41
	v_bcnt_u32_b32 v44, v41, v44
	v_sub_u32_e32 v45, v49, v43
	v_and_b32_e32 v45, 0x80808080, v45
	v_bcnt_u32_b32 v44, v45, v44
	v_sub_u32_e32 v41, v50, v43
	v_and_b32_e32 v41, 0x80808080, v41
	v_bcnt_u32_b32 v44, v41, v44
	v_sub_u32_e32 v45, v51, v43
	v_and_b32_e32 v45, 0x80808080, v45
	v_bcnt_u32_b32 v44, v45, v44
	v_sub_u32_e32 v41, v52, v43
	v_and_b32_e32 v41, 0x80808080, v41
	v_bcnt_u32_b32 v44, v41, v44
	v_sub_u32_e32 v45, v53, v43
	v_and_b32_e32 v45, 0x80808080, v45
	v_bcnt_u32_b32 v44, v45, v44
	v_sub_u32_e32 v41, v54, v43
	v_and_b32_e32 v41, 0x80808080, v41
	v_bcnt_u32_b32 v44, v41, v44
	v_sub_u32_e32 v45, v55, v43
	v_and_b32_e32 v45, 0x80808080, v45
	v_bcnt_u32_b32 v44, v45, v44
	v_mov_b32_e32 v45, v44
	s_nop 1
	v_add_u32_dpp v45, v45, v45 row_ror:1 row_mask:0xf bank_mask:0xf
	s_nop 1
	v_add_u32_dpp v45, v45, v45 row_ror:2 row_mask:0xf bank_mask:0xf
	s_nop 1
	v_add_u32_dpp v45, v45, v45 row_ror:4 row_mask:0xf bank_mask:0xf
	s_nop 1
	v_add_u32_dpp v45, v45, v45 row_ror:8 row_mask:0xf bank_mask:0xf
	s_nop 0
	v_cmp_le_u32_e32 vcc, 0x100, v45
	s_nop 1
	v_cndmask_b32_e32 v36, v36, v42, vcc
	v_cndmask_b32_e32 v46, v46, v45, vcc
	v_cndmask_b32_e32 v47, v47, v44, vcc
	v_or_b32_e32 v42, 0x8080808, v36
	v_subrev_u32_e32 v43, 0x80808080, v42
	v_mov_b32_e32 v44, 0
	v_sub_u32_e32 v41, v48, v43
	v_and_b32_e32 v41, 0x80808080, v41
	v_bcnt_u32_b32 v44, v41, v44
	v_sub_u32_e32 v45, v49, v43
	v_and_b32_e32 v45, 0x80808080, v45
	v_bcnt_u32_b32 v44, v45, v44
	v_sub_u32_e32 v41, v50, v43
	v_and_b32_e32 v41, 0x80808080, v41
	v_bcnt_u32_b32 v44, v41, v44
	v_sub_u32_e32 v45, v51, v43
	v_and_b32_e32 v45, 0x80808080, v45
	v_bcnt_u32_b32 v44, v45, v44
	v_sub_u32_e32 v41, v52, v43
	v_and_b32_e32 v41, 0x80808080, v41
	v_bcnt_u32_b32 v44, v41, v44
	v_sub_u32_e32 v45, v53, v43
	v_and_b32_e32 v45, 0x80808080, v45
	v_bcnt_u32_b32 v44, v45, v44
	v_sub_u32_e32 v41, v54, v43
	v_and_b32_e32 v41, 0x80808080, v41
	v_bcnt_u32_b32 v44, v41, v44
	v_sub_u32_e32 v45, v55, v43
	v_and_b32_e32 v45, 0x80808080, v45
	v_bcnt_u32_b32 v44, v45, v44
	v_mov_b32_e32 v45, v44
	s_nop 1
	v_add_u32_dpp v45, v45, v45 row_ror:1 row_mask:0xf bank_mask:0xf
	s_nop 1
	v_add_u32_dpp v45, v45, v45 row_ror:2 row_mask:0xf bank_mask:0xf
	s_nop 1
	v_add_u32_dpp v45, v45, v45 row_ror:4 row_mask:0xf bank_mask:0xf
	s_nop 1
	v_add_u32_dpp v45, v45, v45 row_ror:8 row_mask:0xf bank_mask:0xf
	s_nop 0
	v_cmp_le_u32_e32 vcc, 0x100, v45
	s_nop 1
	v_cndmask_b32_e32 v36, v36, v42, vcc
	v_cndmask_b32_e32 v46, v46, v45, vcc
	v_cndmask_b32_e32 v47, v47, v44, vcc
	v_or_b32_e32 v42, 0x4040404, v36
	v_subrev_u32_e32 v43, 0x80808080, v42
	v_mov_b32_e32 v44, 0
	v_sub_u32_e32 v41, v48, v43
	v_and_b32_e32 v41, 0x80808080, v41
	v_bcnt_u32_b32 v44, v41, v44
	v_sub_u32_e32 v45, v49, v43
	v_and_b32_e32 v45, 0x80808080, v45
	v_bcnt_u32_b32 v44, v45, v44
	v_sub_u32_e32 v41, v50, v43
	v_and_b32_e32 v41, 0x80808080, v41
	v_bcnt_u32_b32 v44, v41, v44
	v_sub_u32_e32 v45, v51, v43
	v_and_b32_e32 v45, 0x80808080, v45
	v_bcnt_u32_b32 v44, v45, v44
	v_sub_u32_e32 v41, v52, v43
	v_and_b32_e32 v41, 0x80808080, v41
	v_bcnt_u32_b32 v44, v41, v44
	v_sub_u32_e32 v45, v53, v43
	v_and_b32_e32 v45, 0x80808080, v45
	v_bcnt_u32_b32 v44, v45, v44
	v_sub_u32_e32 v41, v54, v43
	v_and_b32_e32 v41, 0x80808080, v41
	v_bcnt_u32_b32 v44, v41, v44
	v_sub_u32_e32 v45, v55, v43
	v_and_b32_e32 v45, 0x80808080, v45
	v_bcnt_u32_b32 v44, v45, v44
	v_mov_b32_e32 v45, v44
	s_nop 1
	v_add_u32_dpp v45, v45, v45 row_ror:1 row_mask:0xf bank_mask:0xf
	s_nop 1
	v_add_u32_dpp v45, v45, v45 row_ror:2 row_mask:0xf bank_mask:0xf
	s_nop 1
	v_add_u32_dpp v45, v45, v45 row_ror:4 row_mask:0xf bank_mask:0xf
	s_nop 1
	v_add_u32_dpp v45, v45, v45 row_ror:8 row_mask:0xf bank_mask:0xf
	s_nop 0
	v_cmp_le_u32_e32 vcc, 0x100, v45
	s_nop 1
	v_cndmask_b32_e32 v36, v36, v42, vcc
	v_cndmask_b32_e32 v46, v46, v45, vcc
	v_cndmask_b32_e32 v47, v47, v44, vcc
	v_or_b32_e32 v42, 0x2020202, v36
	v_subrev_u32_e32 v43, 0x80808080, v42
	v_mov_b32_e32 v44, 0
	v_sub_u32_e32 v41, v48, v43
	v_and_b32_e32 v41, 0x80808080, v41
	v_bcnt_u32_b32 v44, v41, v44
	v_sub_u32_e32 v45, v49, v43
	v_and_b32_e32 v45, 0x80808080, v45
	v_bcnt_u32_b32 v44, v45, v44
	v_sub_u32_e32 v41, v50, v43
	v_and_b32_e32 v41, 0x80808080, v41
	v_bcnt_u32_b32 v44, v41, v44
	v_sub_u32_e32 v45, v51, v43
	v_and_b32_e32 v45, 0x80808080, v45
	v_bcnt_u32_b32 v44, v45, v44
	v_sub_u32_e32 v41, v52, v43
	v_and_b32_e32 v41, 0x80808080, v41
	v_bcnt_u32_b32 v44, v41, v44
	v_sub_u32_e32 v45, v53, v43
	v_and_b32_e32 v45, 0x80808080, v45
	v_bcnt_u32_b32 v44, v45, v44
	v_sub_u32_e32 v41, v54, v43
	v_and_b32_e32 v41, 0x80808080, v41
	v_bcnt_u32_b32 v44, v41, v44
	v_sub_u32_e32 v45, v55, v43
	v_and_b32_e32 v45, 0x80808080, v45
	v_bcnt_u32_b32 v44, v45, v44
	v_mov_b32_e32 v45, v44
	s_nop 1
	v_add_u32_dpp v45, v45, v45 row_ror:1 row_mask:0xf bank_mask:0xf
	s_nop 1
	v_add_u32_dpp v45, v45, v45 row_ror:2 row_mask:0xf bank_mask:0xf
	s_nop 1
	v_add_u32_dpp v45, v45, v45 row_ror:4 row_mask:0xf bank_mask:0xf
	s_nop 1
	v_add_u32_dpp v45, v45, v45 row_ror:8 row_mask:0xf bank_mask:0xf
	s_nop 0
	v_cmp_le_u32_e32 vcc, 0x100, v45
	s_nop 1
	v_cndmask_b32_e32 v36, v36, v42, vcc
	v_cndmask_b32_e32 v46, v46, v45, vcc
	v_cndmask_b32_e32 v47, v47, v44, vcc
	v_or_b32_e32 v42, 0x1010101, v36
	v_subrev_u32_e32 v43, 0x80808080, v42
	v_mov_b32_e32 v44, 0
	v_sub_u32_e32 v41, v48, v43
	v_and_b32_e32 v41, 0x80808080, v41
	v_bcnt_u32_b32 v44, v41, v44
	v_sub_u32_e32 v45, v49, v43
	v_and_b32_e32 v45, 0x80808080, v45
	v_bcnt_u32_b32 v44, v45, v44
	v_sub_u32_e32 v41, v50, v43
	v_and_b32_e32 v41, 0x80808080, v41
	v_bcnt_u32_b32 v44, v41, v44
	v_sub_u32_e32 v45, v51, v43
	v_and_b32_e32 v45, 0x80808080, v45
	v_bcnt_u32_b32 v44, v45, v44
	v_sub_u32_e32 v41, v52, v43
	v_and_b32_e32 v41, 0x80808080, v41
	v_bcnt_u32_b32 v44, v41, v44
	v_sub_u32_e32 v45, v53, v43
	v_and_b32_e32 v45, 0x80808080, v45
	v_bcnt_u32_b32 v44, v45, v44
	v_sub_u32_e32 v41, v54, v43
	v_and_b32_e32 v41, 0x80808080, v41
	v_bcnt_u32_b32 v44, v41, v44
	v_sub_u32_e32 v45, v55, v43
	v_and_b32_e32 v45, 0x80808080, v45
	v_bcnt_u32_b32 v44, v45, v44
	v_mov_b32_e32 v45, v44
	s_nop 1
	v_add_u32_dpp v45, v45, v45 row_ror:1 row_mask:0xf bank_mask:0xf
	s_nop 1
	v_add_u32_dpp v45, v45, v45 row_ror:2 row_mask:0xf bank_mask:0xf
	s_nop 1
	v_add_u32_dpp v45, v45, v45 row_ror:4 row_mask:0xf bank_mask:0xf
	s_nop 1
	v_add_u32_dpp v45, v45, v45 row_ror:8 row_mask:0xf bank_mask:0xf
	s_nop 0
	v_cmp_le_u32_e32 vcc, 0x100, v45
	s_nop 1
	v_cndmask_b32_e32 v36, v36, v42, vcc
	v_cndmask_b32_e32 v46, v46, v45, vcc
	v_cndmask_b32_e32 v47, v47, v44, vcc
	v_and_b32_e32 v41, 0x7f, v36
	v_lshlrev_b32_e32 v41, v39, v41
	v_add_u32_e32 v41, v34, v41
	v_cmp_ge_u32_e32 vcc, 0x120, v46
	v_cmp_eq_u32_e64 s[0:1], 0, v39
	v_lshlrev_b32_e32 v42, v39, v200
	v_add_u32_e32 v42, -1, v42
	s_or_b64 vcc, vcc, s[0:1]
	s_andn2_b64 s[0:1], vcc, s[50:51]
	s_nor_b64 s[2:3], vcc, s[50:51]
	s_or_b64 s[50:51], s[50:51], vcc
	v_add_u32_e64 v42, v41, v42 clamp
	v_min_u32_e32 v42, v42, v35
	v_cndmask_b32_e64 v37, v37, v41, s[0:1]
	v_cndmask_b32_e64 v62, v62, v47, s[0:1]
	v_cndmask_b32_e64 v35, v35, v42, s[2:3]
	v_cndmask_b32_e64 v34, v34, v41, s[2:3]
	s_cmp_eq_u64 s[50:51], -1
	s_cbranch_scc0 .Lp2apr1_iter
	s_mov_b64 exec, s[22:23]
	v_mov_b32_e32 v61, v62
	s_nop 1
	v_add_u32_dpp v61, v61, v61 row_shr:1 row_mask:0xf bank_mask:0xf bound_ctrl:1
	s_nop 1
	v_add_u32_dpp v61, v61, v61 row_shr:2 row_mask:0xf bank_mask:0xf bound_ctrl:1
	s_nop 1
	v_add_u32_dpp v61, v61, v61 row_shr:4 row_mask:0xf bank_mask:0xf bound_ctrl:1
	s_nop 1
	v_add_u32_dpp v61, v61, v61 row_shr:8 row_mask:0xf bank_mask:0xf bound_ctrl:1
	v_sub_u32_e32 v62, v61, v62
	v_lshl_add_u32 v41, v62, 2, v59
	v_add_u32_e32 v41, -4, v41
	v_cmpx_ge_u32_e32 vcc, v0, v37
	v_add_u32_e32 v41, 4, v41
	ds_write_b32 v41, v0
	s_mov_b64 exec, s[22:23]
	v_cmpx_ge_u32_e32 vcc, v1, v37
	v_add_u32_e32 v41, 4, v41
	ds_write_b32 v41, v1
	s_mov_b64 exec, s[22:23]
	v_cmpx_ge_u32_e32 vcc, v2, v37
	v_add_u32_e32 v41, 4, v41
	ds_write_b32 v41, v2
	s_mov_b64 exec, s[22:23]
	v_cmpx_ge_u32_e32 vcc, v3, v37
	v_add_u32_e32 v41, 4, v41
	ds_write_b32 v41, v3
	s_mov_b64 exec, s[22:23]
	v_cmpx_ge_u32_e32 vcc, v4, v37
	v_add_u32_e32 v41, 4, v41
	ds_write_b32 v41, v4
	s_mov_b64 exec, s[22:23]
	v_cmpx_ge_u32_e32 vcc, v5, v37
	v_add_u32_e32 v41, 4, v41
	ds_write_b32 v41, v5
	s_mov_b64 exec, s[22:23]
	v_cmpx_ge_u32_e32 vcc, v6, v37
	v_add_u32_e32 v41, 4, v41
	ds_write_b32 v41, v6
	s_mov_b64 exec, s[22:23]
	v_cmpx_ge_u32_e32 vcc, v7, v37
	v_add_u32_e32 v41, 4, v41
	ds_write_b32 v41, v7
	s_mov_b64 exec, s[22:23]
	v_cmpx_ge_u32_e32 vcc, v8, v37
	v_add_u32_e32 v41, 4, v41
	ds_write_b32 v41, v8
	s_mov_b64 exec, s[22:23]
	v_cmpx_ge_u32_e32 vcc, v9, v37
	v_add_u32_e32 v41, 4, v41
	ds_write_b32 v41, v9
	s_mov_b64 exec, s[22:23]
	v_cmpx_ge_u32_e32 vcc, v10, v37
	v_add_u32_e32 v41, 4, v41
	ds_write_b32 v41, v10
	s_mov_b64 exec, s[22:23]
	v_cmpx_ge_u32_e32 vcc, v11, v37
	v_add_u32_e32 v41, 4, v41
	ds_write_b32 v41, v11
	s_mov_b64 exec, s[22:23]
	v_cmpx_ge_u32_e32 vcc, v12, v37
	v_add_u32_e32 v41, 4, v41
	ds_write_b32 v41, v12
	s_mov_b64 exec, s[22:23]
	v_cmpx_ge_u32_e32 vcc, v13, v37
	v_add_u32_e32 v41, 4, v41
	ds_write_b32 v41, v13
	s_mov_b64 exec, s[22:23]
	v_cmpx_ge_u32_e32 vcc, v14, v37
	v_add_u32_e32 v41, 4, v41
	ds_write_b32 v41, v14
	s_mov_b64 exec, s[22:23]
	v_cmpx_ge_u32_e32 vcc, v15, v37
	v_add_u32_e32 v41, 4, v41
	ds_write_b32 v41, v15
	s_mov_b64 exec, s[22:23]
	v_cmpx_ge_u32_e32 vcc, v16, v37
	v_add_u32_e32 v41, 4, v41
	ds_write_b32 v41, v16
	s_mov_b64 exec, s[22:23]
	v_cmpx_ge_u32_e32 vcc, v17, v37
	v_add_u32_e32 v41, 4, v41
	ds_write_b32 v41, v17
	s_mov_b64 exec, s[22:23]
	v_cmpx_ge_u32_e32 vcc, v18, v37
	v_add_u32_e32 v41, 4, v41
	ds_write_b32 v41, v18
	s_mov_b64 exec, s[22:23]
	v_cmpx_ge_u32_e32 vcc, v19, v37
	v_add_u32_e32 v41, 4, v41
	ds_write_b32 v41, v19
	s_mov_b64 exec, s[22:23]
	v_cmpx_ge_u32_e32 vcc, v20, v37
	v_add_u32_e32 v41, 4, v41
	ds_write_b32 v41, v20
	s_mov_b64 exec, s[22:23]
	v_cmpx_ge_u32_e32 vcc, v21, v37
	v_add_u32_e32 v41, 4, v41
	ds_write_b32 v41, v21
	s_mov_b64 exec, s[22:23]
	v_cmpx_ge_u32_e32 vcc, v22, v37
	v_add_u32_e32 v41, 4, v41
	ds_write_b32 v41, v22
	s_mov_b64 exec, s[22:23]
	v_cmpx_ge_u32_e32 vcc, v23, v37
	v_add_u32_e32 v41, 4, v41
	ds_write_b32 v41, v23
	s_mov_b64 exec, s[22:23]
	v_cmpx_ge_u32_e32 vcc, v24, v37
	v_add_u32_e32 v41, 4, v41
	ds_write_b32 v41, v24
	s_mov_b64 exec, s[22:23]
	v_cmpx_ge_u32_e32 vcc, v25, v37
	v_add_u32_e32 v41, 4, v41
	ds_write_b32 v41, v25
	s_mov_b64 exec, s[22:23]
	v_cmpx_ge_u32_e32 vcc, v26, v37
	v_add_u32_e32 v41, 4, v41
	ds_write_b32 v41, v26
	s_mov_b64 exec, s[22:23]
	v_cmpx_ge_u32_e32 vcc, v27, v37
	v_add_u32_e32 v41, 4, v41
	ds_write_b32 v41, v27
	s_mov_b64 exec, s[22:23]
	v_cmpx_ge_u32_e32 vcc, v28, v37
	v_add_u32_e32 v41, 4, v41
	ds_write_b32 v41, v28
	s_mov_b64 exec, s[22:23]
	v_cmpx_ge_u32_e32 vcc, v29, v37
	v_add_u32_e32 v41, 4, v41
	ds_write_b32 v41, v29
	s_mov_b64 exec, s[22:23]
	v_cmpx_ge_u32_e32 vcc, v30, v37
	v_add_u32_e32 v41, 4, v41
	ds_write_b32 v41, v30
	s_mov_b64 exec, s[22:23]
	v_cmpx_ge_u32_e32 vcc, v31, v37
	v_add_u32_e32 v41, 4, v41
	ds_write_b32 v41, v31
	s_mov_b64 exec, s[22:23]
	s_mov_b64 exec, -1
	v_and_b32_e32 v41, 0xffffe000, v37
	v_ashrrev_i32_e32 v42, 31, v41
	v_not_b32_e32 v42, v42
	v_or_b32_e32 v42, 0x80000000, v42
	v_xor_b32_e32 v63, v41, v42
	s_cmpk_lt_i32 s8, 0x121
	s_cbranch_scc1 .Lp2apr1_o0
	v_readlane_b32 s0, v63, 0
	v_readlane_b32 s74, v37, 0
	v_readlane_b32 s8, v61, 15
	v_mov_b32_e32 v233, s0
